# S2+peel+XL with the attention K/V LDS-DMA in SGPR-base + 32-bit VGPR-offset form (no 64-bit VALU address adds)
# speedup vs baseline: 1.0167x; 1.0167x over previous
.LBB0_275:
	s_or_b64 exec, exec, s[0:1]
	s_ashr_i32 s69, s63, 6
	s_and_b32 s27, s69, 3
	s_lshl_b32 s14, s62, 7
	s_add_i32 s0, s14, s61
	s_lshl_b32 s15, s27, 5
	v_and_b32_e32 v199, 31, v10
	s_or_b32 s0, s15, s0
	v_or_b32_e32 v12, s0, v199
	s_ashr_i32 s26, s63, 8
	v_ashrrev_i32_e32 v13, 31, v12
	v_lshlrev_b64 v[2:3], 11, v[12:13]
	s_lshl_b32 s0, s26, 6
	v_bfe_u32 v198, v10, 5, 1
	v_lshl_add_u64 v[2:3], s[44:45], 0, v[2:3]
	s_ashr_i32 s1, s0, 31
	v_lshl_add_u64 v[2:3], s[0:1], 1, v[2:3]
	v_lshlrev_b32_e32 v0, 4, v198
	v_bfe_u32 v4, v10, 4, 2
	s_lshl_b32 s1, s69, 3
	v_lshl_add_u64 v[2:3], v[2:3], 0, v[0:1]
	v_or_b32_e32 v0, s1, v4
	global_load_dword v200, v1, s[4:5] offset:256
	global_load_dword v201, v1, s[4:5] offset:2812
	global_load_dwordx4 v[130:133], v[2:3], off
	global_load_dwordx4 v[134:137], v[2:3], off offset:32
	global_load_dwordx4 v[138:141], v[2:3], off offset:64
	global_load_dwordx4 v[142:145], v[2:3], off offset:96
	v_add_u32_e32 v2, s61, v0
	v_bitop3_b32 v6, s1, v10, v4 bitop3:0x36
	v_ashrrev_i32_e32 v3, 31, v2
	v_lshlrev_b64 v[2:3], 11, v[2:3]
	v_lshlrev_b32_e32 v0, 4, v6
	v_bfe_u32 v5, v10, 3, 3
	v_and_b32_e32 v0, 0xf0, v0
	v_add_u32_e32 v188, v2, v0
	v_or_b32_e32 v2, s67, v5
	v_lshl_add_u32 v2, s69, 4, v2
	s_lshl_b32 s0, s69, 1
	v_xor_b32_e32 v0, v4, v10
	v_ashrrev_i32_e32 v3, 31, v2
	v_lshlrev_b64 v[2:3], 15, v[2:3]
	v_lshlrev_b32_e32 v0, 4, v0
	s_or_b32 s0, s0, 1
	v_and_b32_e32 v0, 0x70, v0
	s_lshl_b32 s1, s0, 2
	v_add_u32_e32 v190, v2, v0
	v_or_b32_e32 v0, s1, v4
	v_add_u32_e32 v2, s61, v0
	v_bitop3_b32 v4, s1, v10, v4 bitop3:0x36
	v_ashrrev_i32_e32 v3, 31, v2
	v_lshlrev_b64 v[2:3], 11, v[2:3]
	v_lshlrev_b32_e32 v0, 4, v4
	v_and_b32_e32 v0, 0xf0, v0
	v_add_u32_e32 v192, v2, v0
	v_lshl_or_b32 v0, s0, 3, v5
	v_lshrrev_b32_e32 v2, 1, v0
	v_xor_b32_e32 v4, v2, v10
	v_add_u32_e32 v2, s67, v0
	v_ashrrev_i32_e32 v3, 31, v2
	v_lshlrev_b64 v[2:3], 15, v[2:3]
	v_lshlrev_b32_e32 v0, 4, v4
	s_lshl_b32 s0, s69, 11
	v_and_b32_e32 v0, 0x70, v0
	s_add_i32 s70, s0, 0
	s_mov_b32 s29, s23
	v_add_u32_e32 v194, v2, v0
	s_add_u32 s100, s46, s28
	s_addc_u32 s101, s47, 0
	s_mov_b32 m0, s70
	s_add_i32 s71, s70, 0x8000
	global_load_lds_dwordx4 v188, s[100:101]
	s_add_i32 s29, s70, 0x400
	s_mov_b32 m0, s29
	s_lshl_b64 s[0:1], s[34:35], 1
	global_load_lds_dwordx4 v192, s[100:101]
	s_add_u32 s100, s50, s0
	s_addc_u32 s101, s51, s1
	s_mov_b32 m0, s71
	s_add_i32 s72, s70, 0x8400
	global_load_lds_dwordx4 v190, s[100:101]
	s_mov_b32 m0, s72
	s_add_i32 s73, s70, 0x4000
	s_mov_b32 s31, s23
	global_load_lds_dwordx4 v194, s[100:101]
	s_add_u32 s100, s46, s30
	s_addc_u32 s101, s47, 0
	s_mov_b32 m0, s73
	v_and_b32_e32 v0, 19, v10
	global_load_lds_dwordx4 v188, s[100:101]
	s_add_i32 s31, s70, 0x4400
	s_mov_b32 m0, s31
	v_lshrrev_b32_e32 v11, 1, v10
	global_load_lds_dwordx4 v192, s[100:101]
	v_lshlrev_b32_e32 v2, 1, v10
	v_and_or_b32 v17, v2, 8, v0
	v_and_b32_e32 v18, 4, v11
	v_or_b32_e32 v2, v17, v18
	v_lshl_or_b32 v14, s26, 3, v198
	v_lshlrev_b32_e32 v0, 8, v2
	v_bitop3_b32 v2, v2, v14, 15 bitop3:0x6c
	s_or_b32 s14, s15, s14
	v_lshl_add_u32 v2, v2, 4, v0
	s_add_i32 s74, s14, 0xffffffa5
	v_add_u32_e32 v202, 0, v2
	s_cmp_gt_i32 s65, s74
	s_waitcnt vmcnt(0)
	s_waitcnt vmcnt(0) lgkmcnt(0)
	s_barrier
	ds_read_b128 v[6:9], v202
	ds_read_b128 v[2:5], v202 offset:8192
	s_cselect_b64 s[0:1], -1, 0
	s_add_i32 s75, s14, 0x7a
	s_cmp_lt_i32 s34, s75
	s_cselect_b64 s[40:41], -1, 0
	s_and_b64 s[0:1], s[0:1], s[40:41]
	s_andn2_b64 vcc, exec, s[0:1]
	s_mov_b64 s[0:1], -1
	s_cbranch_vccz .LBB0_277
	s_waitcnt lgkmcnt(1)
	v_mfma_f32_32x32x16_bf16 v[66:81], v[6:9], v[130:133], 0
	s_mov_b64 s[0:1], 0
	s_waitcnt lgkmcnt(0)
	v_mfma_f32_32x32x16_bf16 v[82:97], v[2:5], v[130:133], 0

.LBB0_280:
	s_waitcnt lgkmcnt(5)
	v_mfma_f32_32x32x16_bf16 v[66:81], v[166:169], v[134:137], v[66:81]
	v_add_f32_e32 v174, v114, v115
	v_add_f32_e32 v175, v116, v117
	v_add_f32_e32 v176, v118, v119
	v_add_f32_e32 v177, v120, v121
	v_add_f32_e32 v174, v174, v122
	s_waitcnt lgkmcnt(4)
	v_mfma_f32_32x32x16_bf16 v[82:97], v[162:165], v[134:137], v[82:97]
	v_add_f32_e32 v175, v175, v123
	v_add_f32_e32 v176, v176, v124
	v_add_f32_e32 v177, v177, v125
	v_add_f32_e32 v174, v174, v126
	v_add_f32_e32 v175, v175, v127
	s_waitcnt lgkmcnt(3)
	v_mfma_f32_32x32x16_bf16 v[66:81], v[158:161], v[138:141], v[66:81]
	v_add_f32_e32 v176, v176, v128
	v_add_f32_e32 v177, v177, v129
	v_add_f32_e32 v174, v174, v98
	v_add_f32_e32 v175, v175, v99
	v_add_f32_e32 v176, v176, v100
	s_waitcnt lgkmcnt(2)
	v_mfma_f32_32x32x16_bf16 v[82:97], v[154:157], v[138:141], v[82:97]
	v_add_f32_e32 v177, v177, v101
	v_add_f32_e32 v174, v174, v102
	v_add_f32_e32 v175, v175, v103
	v_add_f32_e32 v176, v176, v104
	v_add_f32_e32 v177, v177, v105
	s_waitcnt lgkmcnt(1)
	v_mfma_f32_32x32x16_bf16 v[66:81], v[150:153], v[142:145], v[66:81]
	v_add_f32_e32 v174, v174, v106
	v_add_f32_e32 v175, v175, v107
	v_add_f32_e32 v176, v176, v108
	v_add_f32_e32 v177, v177, v109
	s_waitcnt lgkmcnt(0)
	v_mfma_f32_32x32x16_bf16 v[82:97], v[146:149], v[142:145], v[82:97]
	v_add_f32_e32 v174, v174, v110
	v_add_f32_e32 v175, v175, v111
	v_add_f32_e32 v176, v176, v112
	v_add_f32_e32 v177, v177, v113
	v_add_f32_e32 v174, v174, v175
	v_add_f32_e32 v176, v176, v177
	v_cvt_pk_bf16_f32 v113, v112, v113
	v_cvt_pk_bf16_f32 v112, v110, v111
	v_cvt_pk_bf16_f32 v111, v108, v109
	v_cvt_pk_bf16_f32 v110, v106, v107
	v_add_f32_e32 v174, v174, v176
	v_cvt_pk_bf16_f32 v109, v104, v105
	v_cvt_pk_bf16_f32 v108, v102, v103
	v_cvt_pk_bf16_f32 v107, v100, v101
	v_cvt_pk_bf16_f32 v106, v98, v99
	v_cvt_pk_bf16_f32 v98, v114, v115
	v_cvt_pk_bf16_f32 v99, v116, v117
	v_cvt_pk_bf16_f32 v100, v118, v119
	v_cvt_pk_bf16_f32 v101, v120, v121
	v_cvt_pk_bf16_f32 v102, v122, v123
	v_cvt_pk_bf16_f32 v103, v124, v125
	v_cvt_pk_bf16_f32 v104, v126, v127
	v_cvt_pk_bf16_f32 v105, v128, v129
	v_add_f32_e32 v213, v174, v0
	ds_read_b128 v[114:117], v208 offset:49152
	ds_read_b128 v[118:121], v208 offset:53248
	ds_read_b128 v[122:125], v208 offset:57344
	ds_read_b128 v[126:129], v208 offset:61440
	ds_read_b128 v[150:153], v209 offset:53248
	ds_read_b128 v[146:149], v209 offset:49152
	ds_read_b128 v[154:157], v209 offset:57344
	ds_read_b128 v[158:161], v209 offset:61440
	s_and_b32 s0, s77, 0x3f0000
	s_lshl_b32 s22, s0, 1
	s_mov_b32 m0, s73
	s_add_u32 s100, s46, s22
	s_addc_u32 s101, s47, 0
	global_load_lds_dwordx4 v188, s[100:101]
	s_nop 0
	s_mov_b32 m0, s31
	s_lshl_b32 s22, s15, 1
	global_load_lds_dwordx4 v192, s[100:101]
	s_add_u32 s100, s50, s22
	s_addc_u32 s101, s51, 0
	s_mov_b32 m0, s71
	global_load_lds_dwordx4 v190, s[100:101]
	s_nop 0
	s_mov_b32 m0, s72
	s_nop 0
	global_load_lds_dwordx4 v194, s[100:101]
	s_waitcnt lgkmcnt(0)
	v_mfma_f32_32x32x16_bf16 v[50:65], v[98:101], v[114:117], v[50:65]
	ds_read_b128 v[114:117], v210 offset:53248
	v_exp_f32_e32 v66, v66
	v_exp_f32_e32 v67, v67
	v_mfma_f32_32x32x16_bf16 v[34:49], v[98:101], v[118:121], v[34:49]
	ds_read_b128 v[118:121], v210 offset:57344
	v_exp_f32_e32 v68, v68
	v_exp_f32_e32 v69, v69
	v_mfma_f32_32x32x16_bf16 v[18:33], v[98:101], v[122:125], v[18:33]
	ds_read_b128 v[122:125], v210 offset:61440
	v_exp_f32_e32 v70, v70
	v_exp_f32_e32 v71, v71
	v_mfma_f32_32x32x16_bf16 v[2:17], v[98:101], v[126:129], v[2:17]
	ds_read_b128 v[98:101], v210 offset:49152
	v_exp_f32_e32 v72, v72
	v_exp_f32_e32 v73, v73
	v_mfma_f32_32x32x16_bf16 v[50:65], v[102:105], v[146:149], v[50:65]
	ds_read_b128 v[126:129], v212 offset:53248
	v_exp_f32_e32 v74, v74
	v_exp_f32_e32 v75, v75
	v_mfma_f32_32x32x16_bf16 v[34:49], v[102:105], v[150:153], v[34:49]
	ds_read_b128 v[146:149], v212 offset:57344
	v_exp_f32_e32 v76, v76
	v_exp_f32_e32 v77, v77
	v_mfma_f32_32x32x16_bf16 v[18:33], v[102:105], v[154:157], v[18:33]
	ds_read_b128 v[150:153], v212 offset:61440
	v_exp_f32_e32 v78, v78
	v_exp_f32_e32 v79, v79
	v_mfma_f32_32x32x16_bf16 v[2:17], v[102:105], v[158:161], v[2:17]
	ds_read_b128 v[102:105], v212 offset:49152
	v_exp_f32_e32 v80, v80
	v_exp_f32_e32 v81, v81
	s_waitcnt lgkmcnt(0)
	v_mfma_f32_32x32x16_bf16 v[50:65], v[106:109], v[98:101], v[50:65]
	v_exp_f32_e32 v82, v82
	v_exp_f32_e32 v83, v83
	v_mfma_f32_32x32x16_bf16 v[34:49], v[106:109], v[114:117], v[34:49]
	v_exp_f32_e32 v84, v84
	v_exp_f32_e32 v85, v85
	v_mfma_f32_32x32x16_bf16 v[18:33], v[106:109], v[118:121], v[18:33]
	v_exp_f32_e32 v86, v86
	v_exp_f32_e32 v87, v87
	v_mfma_f32_32x32x16_bf16 v[2:17], v[106:109], v[122:125], v[2:17]
	v_exp_f32_e32 v88, v88
	v_exp_f32_e32 v89, v89
	v_mfma_f32_32x32x16_bf16 v[50:65], v[110:113], v[102:105], v[50:65]
	v_exp_f32_e32 v90, v90
	v_exp_f32_e32 v91, v91
	v_mfma_f32_32x32x16_bf16 v[34:49], v[110:113], v[126:129], v[34:49]
	v_exp_f32_e32 v92, v92
	v_exp_f32_e32 v93, v93
	v_mfma_f32_32x32x16_bf16 v[18:33], v[110:113], v[146:149], v[18:33]
	v_exp_f32_e32 v94, v94
	v_exp_f32_e32 v95, v95
	v_mfma_f32_32x32x16_bf16 v[2:17], v[110:113], v[150:153], v[2:17]
	v_exp_f32_e32 v96, v96
	v_exp_f32_e32 v97, v97
	s_waitcnt vmcnt(0)
	s_add_i32 s76, s76, 2
	s_add_i32 s77, s77, 0x20000
	s_cmp_gt_u32 s76, 61
	s_waitcnt vmcnt(0)
	s_barrier
	s_cbranch_scc1 .LBB0_295

.LBB0_288:
	s_waitcnt lgkmcnt(5)
	v_mfma_f32_32x32x16_bf16 v[114:129], v[166:169], v[134:137], v[114:129]
	v_add_f32_e32 v174, v66, v67
	v_add_f32_e32 v175, v68, v69
	v_add_f32_e32 v176, v70, v71
	v_add_f32_e32 v177, v72, v73
	v_add_f32_e32 v174, v174, v74
	s_waitcnt lgkmcnt(4)
	v_mfma_f32_32x32x16_bf16 v[98:113], v[162:165], v[134:137], v[98:113]
	v_add_f32_e32 v175, v175, v75
	v_add_f32_e32 v176, v176, v76
	v_add_f32_e32 v177, v177, v77
	v_add_f32_e32 v174, v174, v78
	v_add_f32_e32 v175, v175, v79
	s_waitcnt lgkmcnt(3)
	v_mfma_f32_32x32x16_bf16 v[114:129], v[158:161], v[138:141], v[114:129]
	v_add_f32_e32 v176, v176, v80
	v_add_f32_e32 v177, v177, v81
	v_add_f32_e32 v174, v174, v82
	v_add_f32_e32 v175, v175, v83
	v_add_f32_e32 v176, v176, v84
	s_waitcnt lgkmcnt(2)
	v_mfma_f32_32x32x16_bf16 v[98:113], v[154:157], v[138:141], v[98:113]
	v_add_f32_e32 v177, v177, v85
	v_add_f32_e32 v174, v174, v86
	v_add_f32_e32 v175, v175, v87
	v_add_f32_e32 v176, v176, v88
	v_add_f32_e32 v177, v177, v89
	s_waitcnt lgkmcnt(1)
	v_mfma_f32_32x32x16_bf16 v[114:129], v[150:153], v[142:145], v[114:129]
	v_add_f32_e32 v174, v174, v90
	v_add_f32_e32 v175, v175, v91
	v_add_f32_e32 v176, v176, v92
	v_add_f32_e32 v177, v177, v93
	s_waitcnt lgkmcnt(0)
	v_mfma_f32_32x32x16_bf16 v[98:113], v[146:149], v[142:145], v[98:113]
	v_add_f32_e32 v174, v174, v94
	v_add_f32_e32 v175, v175, v95
	v_add_f32_e32 v176, v176, v96
	v_add_f32_e32 v177, v177, v97
	v_add_f32_e32 v174, v174, v175
	v_add_f32_e32 v176, v176, v177
	v_cvt_pk_bf16_f32 v66, v66, v67
	v_cvt_pk_bf16_f32 v67, v68, v69
	v_cvt_pk_bf16_f32 v68, v70, v71
	v_cvt_pk_bf16_f32 v69, v72, v73
	v_add_f32_e32 v174, v174, v176
	v_cvt_pk_bf16_f32 v70, v74, v75
	v_cvt_pk_bf16_f32 v71, v76, v77
	v_cvt_pk_bf16_f32 v72, v78, v79
	v_cvt_pk_bf16_f32 v73, v80, v81
	v_cvt_pk_bf16_f32 v74, v82, v83
	v_cvt_pk_bf16_f32 v75, v84, v85
	v_cvt_pk_bf16_f32 v76, v86, v87
	v_cvt_pk_bf16_f32 v77, v88, v89
	v_cvt_pk_bf16_f32 v78, v90, v91
	v_cvt_pk_bf16_f32 v79, v92, v93
	v_cvt_pk_bf16_f32 v80, v94, v95
	v_cvt_pk_bf16_f32 v81, v96, v97
	v_add_f32_e32 v0, v174, v213
	ds_read_b128 v[82:85], v208 offset:32768
	ds_read_b128 v[86:89], v208 offset:36864
	ds_read_b128 v[90:93], v208 offset:40960
	ds_read_b128 v[94:97], v208 offset:45056
	ds_read_b128 v[146:149], v209 offset:32768
	ds_read_b128 v[150:153], v209 offset:36864
	ds_read_b128 v[154:157], v209 offset:40960
	ds_read_b128 v[158:161], v209 offset:45056
	s_add_i32 s14, s77, 0xffff0000
	s_and_b32 s14, s14, 0x3e0000
	s_lshl_b32 s22, s14, 1
	s_mov_b32 m0, s70
	s_add_u32 s100, s46, s22
	s_addc_u32 s101, s47, 0
	global_load_lds_dwordx4 v188, s[100:101]
	s_nop 0
	s_mov_b32 m0, s29
	s_lshl_b32 s22, s80, 1
	global_load_lds_dwordx4 v192, s[100:101]
	s_add_u32 s100, s50, s22
	s_addc_u32 s101, s51, 0
	s_add_i32 m0, s70, 0xc000
	global_load_lds_dwordx4 v190, s[100:101]
	s_nop 0
	s_add_i32 m0, s70, 0xc400
	s_nop 0
	global_load_lds_dwordx4 v194, s[100:101]
	s_waitcnt lgkmcnt(0)
	v_mfma_f32_32x32x16_bf16 v[50:65], v[66:69], v[82:85], v[50:65]
	ds_read_b128 v[82:85], v210 offset:32768
	v_exp_f32_e32 v114, v114
	v_exp_f32_e32 v115, v115
	v_mfma_f32_32x32x16_bf16 v[34:49], v[66:69], v[86:89], v[34:49]
	ds_read_b128 v[86:89], v210 offset:36864
	v_exp_f32_e32 v116, v116
	v_exp_f32_e32 v117, v117
	v_mfma_f32_32x32x16_bf16 v[18:33], v[66:69], v[90:93], v[18:33]
	ds_read_b128 v[90:93], v210 offset:40960
	v_exp_f32_e32 v118, v118
	v_exp_f32_e32 v119, v119
	v_mfma_f32_32x32x16_bf16 v[2:17], v[66:69], v[94:97], v[2:17]
	ds_read_b128 v[66:69], v210 offset:45056
	v_exp_f32_e32 v120, v120
	v_exp_f32_e32 v121, v121
	v_mfma_f32_32x32x16_bf16 v[50:65], v[70:73], v[146:149], v[50:65]
	ds_read_b128 v[94:97], v212 offset:32768
	v_exp_f32_e32 v122, v122
	v_exp_f32_e32 v123, v123
	v_mfma_f32_32x32x16_bf16 v[34:49], v[70:73], v[150:153], v[34:49]
	ds_read_b128 v[146:149], v212 offset:36864
	v_exp_f32_e32 v124, v124
	v_exp_f32_e32 v125, v125
	v_mfma_f32_32x32x16_bf16 v[18:33], v[70:73], v[154:157], v[18:33]
	ds_read_b128 v[150:153], v212 offset:40960
	v_exp_f32_e32 v126, v126
	v_exp_f32_e32 v127, v127
	v_mfma_f32_32x32x16_bf16 v[2:17], v[70:73], v[158:161], v[2:17]
	ds_read_b128 v[70:73], v212 offset:45056
	v_exp_f32_e32 v128, v128
	v_exp_f32_e32 v129, v129
	s_waitcnt lgkmcnt(0)
	v_mfma_f32_32x32x16_bf16 v[50:65], v[74:77], v[82:85], v[50:65]
	v_exp_f32_e32 v98, v98
	v_exp_f32_e32 v99, v99
	v_mfma_f32_32x32x16_bf16 v[34:49], v[74:77], v[86:89], v[34:49]
	v_exp_f32_e32 v100, v100
	v_exp_f32_e32 v101, v101
	v_mfma_f32_32x32x16_bf16 v[18:33], v[74:77], v[90:93], v[18:33]
	v_exp_f32_e32 v102, v102
	v_exp_f32_e32 v103, v103
	v_mfma_f32_32x32x16_bf16 v[2:17], v[74:77], v[66:69], v[2:17]
	v_exp_f32_e32 v104, v104
	v_exp_f32_e32 v105, v105
	v_mfma_f32_32x32x16_bf16 v[50:65], v[78:81], v[94:97], v[50:65]
	v_exp_f32_e32 v106, v106
	v_exp_f32_e32 v107, v107
	v_mfma_f32_32x32x16_bf16 v[34:49], v[78:81], v[146:149], v[34:49]
	v_exp_f32_e32 v108, v108
	v_exp_f32_e32 v109, v109
	v_mfma_f32_32x32x16_bf16 v[18:33], v[78:81], v[150:153], v[18:33]
	v_exp_f32_e32 v110, v110
	v_exp_f32_e32 v111, v111
	v_mfma_f32_32x32x16_bf16 v[2:17], v[78:81], v[70:73], v[2:17]
	v_exp_f32_e32 v112, v112
	v_exp_f32_e32 v113, v113
	s_and_b64 s[0:1], s[0:1], exec
	s_waitcnt vmcnt(0)
	s_cselect_b32 s14, 1, 2
	s_and_b64 s[0:1], s[40:41], exec
	s_cselect_b32 s14, s14, 0
	s_cmp_eq_u32 s14, s79
	s_waitcnt vmcnt(0)
	s_barrier
	s_cbranch_scc1 .LBB0_290
	s_cmp_eq_u32 s79, 0
	s_cselect_b64 vcc, -1, 0
	s_cmp_eq_u32 s79, 2
	s_cselect_b64 s[0:1], -1, 0
	v_cndmask_b32_e64 v66, 0, v201, s[0:1]
	s_cmp_eq_u32 s14, 2
	v_cndmask_b32_e32 v66, v66, v200, vcc
	s_cselect_b64 vcc, -1, 0
	v_cndmask_b32_e32 v67, 0, v201, vcc
	v_cndmask_b32_e64 v67, v200, v67, s[40:41]
	v_sub_f32_e32 v66, v66, v67
	v_exp_f32_e32 v66, v66
	s_nop 0
	v_pk_mul_f32 v[64:65], v[66:67], v[64:65] op_sel_hi:[0,1]
	v_pk_mul_f32 v[62:63], v[66:67], v[62:63] op_sel_hi:[0,1]
	v_pk_mul_f32 v[60:61], v[66:67], v[60:61] op_sel_hi:[0,1]
	v_pk_mul_f32 v[58:59], v[66:67], v[58:59] op_sel_hi:[0,1]
	v_pk_mul_f32 v[56:57], v[66:67], v[56:57] op_sel_hi:[0,1]
	v_pk_mul_f32 v[54:55], v[66:67], v[54:55] op_sel_hi:[0,1]
	v_pk_mul_f32 v[52:53], v[66:67], v[52:53] op_sel_hi:[0,1]
	v_pk_mul_f32 v[50:51], v[66:67], v[50:51] op_sel_hi:[0,1]
	v_pk_mul_f32 v[48:49], v[66:67], v[48:49] op_sel_hi:[0,1]
	v_pk_mul_f32 v[46:47], v[66:67], v[46:47] op_sel_hi:[0,1]
	v_pk_mul_f32 v[44:45], v[66:67], v[44:45] op_sel_hi:[0,1]
	v_pk_mul_f32 v[42:43], v[66:67], v[42:43] op_sel_hi:[0,1]
	v_pk_mul_f32 v[40:41], v[66:67], v[40:41] op_sel_hi:[0,1]
	v_pk_mul_f32 v[38:39], v[66:67], v[38:39] op_sel_hi:[0,1]
	v_pk_mul_f32 v[36:37], v[66:67], v[36:37] op_sel_hi:[0,1]
	v_pk_mul_f32 v[34:35], v[66:67], v[34:35] op_sel_hi:[0,1]
	v_pk_mul_f32 v[32:33], v[66:67], v[32:33] op_sel_hi:[0,1]
	v_pk_mul_f32 v[30:31], v[66:67], v[30:31] op_sel_hi:[0,1]
	v_pk_mul_f32 v[28:29], v[66:67], v[28:29] op_sel_hi:[0,1]
	v_pk_mul_f32 v[26:27], v[66:67], v[26:27] op_sel_hi:[0,1]
	v_pk_mul_f32 v[24:25], v[66:67], v[24:25] op_sel_hi:[0,1]
	v_pk_mul_f32 v[22:23], v[66:67], v[22:23] op_sel_hi:[0,1]
	v_pk_mul_f32 v[20:21], v[66:67], v[20:21] op_sel_hi:[0,1]
	v_pk_mul_f32 v[18:19], v[66:67], v[18:19] op_sel_hi:[0,1]
	v_pk_mul_f32 v[16:17], v[66:67], v[16:17] op_sel_hi:[0,1]
	v_pk_mul_f32 v[14:15], v[66:67], v[14:15] op_sel_hi:[0,1]
	v_pk_mul_f32 v[12:13], v[66:67], v[12:13] op_sel_hi:[0,1]
	v_pk_mul_f32 v[10:11], v[66:67], v[10:11] op_sel_hi:[0,1]
	v_pk_mul_f32 v[8:9], v[66:67], v[8:9] op_sel_hi:[0,1]
	v_pk_mul_f32 v[6:7], v[66:67], v[6:7] op_sel_hi:[0,1]
	v_pk_mul_f32 v[4:5], v[66:67], v[4:5] op_sel_hi:[0,1]
	v_pk_mul_f32 v[2:3], v[66:67], v[2:3] op_sel_hi:[0,1]
	v_mul_f32_e32 v0, v0, v66
	s_branch .LBB0_291

.Llast_odd:
	v_add_f32_e32 v174, v114, v115
	v_add_f32_e32 v175, v116, v117
	v_add_f32_e32 v176, v118, v119
	v_add_f32_e32 v177, v120, v121
	v_add_f32_e32 v174, v174, v122
	v_add_f32_e32 v175, v175, v123
	v_add_f32_e32 v176, v176, v124
	v_add_f32_e32 v177, v177, v125
	v_add_f32_e32 v174, v174, v126
	v_add_f32_e32 v175, v175, v127
	v_add_f32_e32 v176, v176, v128
	v_add_f32_e32 v177, v177, v129
	v_add_f32_e32 v174, v174, v98
	v_add_f32_e32 v175, v175, v99
	v_add_f32_e32 v176, v176, v100
	v_add_f32_e32 v177, v177, v101
	v_add_f32_e32 v174, v174, v102
	v_add_f32_e32 v175, v175, v103
	v_add_f32_e32 v176, v176, v104
	v_add_f32_e32 v177, v177, v105
	v_add_f32_e32 v174, v174, v106
	v_add_f32_e32 v175, v175, v107
	v_add_f32_e32 v176, v176, v108
	v_add_f32_e32 v177, v177, v109
	v_add_f32_e32 v174, v174, v110
	v_add_f32_e32 v175, v175, v111
	v_add_f32_e32 v176, v176, v112
	v_add_f32_e32 v177, v177, v113
	v_add_f32_e32 v174, v174, v175
	v_add_f32_e32 v176, v176, v177
	v_cvt_pk_bf16_f32 v113, v112, v113
	v_cvt_pk_bf16_f32 v112, v110, v111
	v_cvt_pk_bf16_f32 v111, v108, v109
	v_cvt_pk_bf16_f32 v110, v106, v107
	v_add_f32_e32 v174, v174, v176
	v_cvt_pk_bf16_f32 v109, v104, v105
	v_cvt_pk_bf16_f32 v108, v102, v103
	v_cvt_pk_bf16_f32 v107, v100, v101
	v_cvt_pk_bf16_f32 v106, v98, v99
	v_cvt_pk_bf16_f32 v98, v114, v115
	v_cvt_pk_bf16_f32 v99, v116, v117
	v_cvt_pk_bf16_f32 v100, v118, v119
	v_cvt_pk_bf16_f32 v101, v120, v121
	v_cvt_pk_bf16_f32 v102, v122, v123
	v_cvt_pk_bf16_f32 v103, v124, v125
	v_cvt_pk_bf16_f32 v104, v126, v127
	v_cvt_pk_bf16_f32 v105, v128, v129
	v_add_f32_e32 v213, v174, v0
	ds_read_b128 v[114:117], v208 offset:49152
	ds_read_b128 v[118:121], v208 offset:53248
	ds_read_b128 v[122:125], v208 offset:57344
	ds_read_b128 v[126:129], v208 offset:61440
	ds_read_b128 v[150:153], v209 offset:53248
	ds_read_b128 v[146:149], v209 offset:49152
	ds_read_b128 v[154:157], v209 offset:57344
	ds_read_b128 v[158:161], v209 offset:61440
	s_add_u32 s100, s46, s22
	s_addc_u32 s101, s47, 0
	s_add_u32 s100, s50, s22
	s_addc_u32 s101, s51, 0
	s_waitcnt lgkmcnt(0)
	v_mfma_f32_32x32x16_bf16 v[50:65], v[98:101], v[114:117], v[50:65]
	ds_read_b128 v[114:117], v210 offset:53248
	v_mfma_f32_32x32x16_bf16 v[34:49], v[98:101], v[118:121], v[34:49]
	ds_read_b128 v[118:121], v210 offset:57344
	v_mfma_f32_32x32x16_bf16 v[18:33], v[98:101], v[122:125], v[18:33]
	ds_read_b128 v[122:125], v210 offset:61440
	v_mfma_f32_32x32x16_bf16 v[2:17], v[98:101], v[126:129], v[2:17]
	ds_read_b128 v[98:101], v210 offset:49152
	v_mfma_f32_32x32x16_bf16 v[50:65], v[102:105], v[146:149], v[50:65]
	ds_read_b128 v[126:129], v212 offset:53248
	v_mfma_f32_32x32x16_bf16 v[34:49], v[102:105], v[150:153], v[34:49]
	ds_read_b128 v[146:149], v212 offset:57344
	v_mfma_f32_32x32x16_bf16 v[18:33], v[102:105], v[154:157], v[18:33]
	ds_read_b128 v[150:153], v212 offset:61440
	v_mfma_f32_32x32x16_bf16 v[2:17], v[102:105], v[158:161], v[2:17]
	ds_read_b128 v[102:105], v212 offset:49152
	s_waitcnt lgkmcnt(0)
	v_mfma_f32_32x32x16_bf16 v[50:65], v[106:109], v[98:101], v[50:65]
	v_mfma_f32_32x32x16_bf16 v[34:49], v[106:109], v[114:117], v[34:49]
	v_mfma_f32_32x32x16_bf16 v[18:33], v[106:109], v[118:121], v[18:33]
	v_mfma_f32_32x32x16_bf16 v[2:17], v[106:109], v[122:125], v[2:17]
	v_mfma_f32_32x32x16_bf16 v[50:65], v[110:113], v[102:105], v[50:65]
	v_mfma_f32_32x32x16_bf16 v[34:49], v[110:113], v[126:129], v[34:49]
	v_mfma_f32_32x32x16_bf16 v[18:33], v[110:113], v[146:149], v[18:33]
	v_mfma_f32_32x32x16_bf16 v[2:17], v[110:113], v[150:153], v[2:17]
	s_barrier
	s_waitcnt vmcnt(0)
	s_branch .LBB0_295
